# grid barrier: last-arriving XCC leader releases every XCC generation word itself; other leaders wait on their own word (no relay hop)
# baseline (speedup 1.0000x reference)
.LBB0_64:
	s_or_b64 exec, exec, s[6:7]
	v_cvt_f32_u32_e32 v5, v2
	s_waitcnt vmcnt(0)
	v_readfirstlane_b32 s4, v4
	s_add_u32 s6, s2, 0x2400
	s_addc_u32 s7, s3, 0
	v_rcp_iflag_f32_e32 v5, v5
	v_add_u32_e32 v3, s4, v3
	v_add_u32_e32 v6, 1, v3
	s_mov_b64 s[8:9], -1
	v_mul_f32_e32 v4, 0x4f7ffffe, v5
	v_cvt_u32_f32_e32 v4, v4
	v_sub_u32_e32 v5, 0, v2
	v_mul_lo_u32 v5, v5, v4
	v_mul_hi_u32 v5, v4, v5
	v_add_u32_e32 v4, v4, v5
	v_mul_hi_u32 v4, v3, v4
	v_mul_lo_u32 v5, v4, v2
	v_sub_u32_e32 v3, v3, v5
	v_add_u32_e32 v7, 1, v4
	v_cmp_ge_u32_e32 vcc, v3, v2
	v_sub_u32_e32 v5, v3, v2
	s_nop 0
	v_cndmask_b32_e32 v4, v4, v7, vcc
	v_cndmask_b32_e32 v3, v3, v5, vcc
	v_add_u32_e32 v5, 1, v4
	v_cmp_ge_u32_e32 vcc, v3, v2
	s_nop 1
	v_cndmask_b32_e32 v4, v4, v5, vcc
	v_mul_lo_u32 v3, v2, v4
	v_add_u32_e32 v2, v3, v2
	v_cmp_ne_u32_e32 vcc, v6, v2
	v_mov_b64_e32 v[2:3], s[6:7]
	s_and_saveexec_b64 s[4:5], vcc
	s_cbranch_execz .LBB0_76
	v_mov_b32_e32 v2, 0
	global_load_dword v3, v2, s[6:7] sc1
	s_mov_b64 s[14:15], 0
	s_waitcnt vmcnt(0)
	v_cmp_eq_u32_e32 vcc, v3, v4
	s_and_saveexec_b64 s[12:13], vcc
	s_cbranch_execz .LBB0_75
	s_add_u32 s8, s82, 0x4200
	s_addc_u32 s9, s83, 0
	s_mov_b32 s24, 1
	s_branch .LBB0_68

.LBB0_76:
	s_or_b64 exec, exec, s[4:5]
	s_and_saveexec_b64 s[4:5], s[8:9]
	s_cbranch_execz .LBB0_78
	v_mov_b32_e32 v4, 1
	v_mov_b32_e32 v2, 0x2000
	global_atomic_add v2, v4, s[66:67] offset:1024
	v_add_u32_e32 v2, 0x100, v2
	global_atomic_add v2, v4, s[66:67] offset:1024
	v_add_u32_e32 v2, 0x100, v2
	global_atomic_add v2, v4, s[66:67] offset:1024
	v_add_u32_e32 v2, 0x100, v2
	global_atomic_add v2, v4, s[66:67] offset:1024
	v_add_u32_e32 v2, 0x100, v2
	global_atomic_add v2, v4, s[66:67] offset:1024
	v_add_u32_e32 v2, 0x100, v2
	global_atomic_add v2, v4, s[66:67] offset:1024
	v_add_u32_e32 v2, 0x100, v2
	global_atomic_add v2, v4, s[66:67] offset:1024
	v_add_u32_e32 v2, 0x100, v2
	global_atomic_add v2, v4, s[66:67] offset:1024
	v_add_u32_e32 v2, 0x100, v2
	global_atomic_add v2, v4, s[66:67] offset:1024
	v_add_u32_e32 v2, 0x100, v2
	global_atomic_add v2, v4, s[66:67] offset:1024
	v_add_u32_e32 v2, 0x100, v2
	global_atomic_add v2, v4, s[66:67] offset:1024
	v_add_u32_e32 v2, 0x100, v2
	global_atomic_add v2, v4, s[66:67] offset:1024
	v_add_u32_e32 v2, 0x100, v2
	global_atomic_add v2, v4, s[66:67] offset:1024
	v_add_u32_e32 v2, 0x100, v2
	global_atomic_add v2, v4, s[66:67] offset:1024
	v_add_u32_e32 v2, 0x100, v2
	global_atomic_add v2, v4, s[66:67] offset:1024
	v_add_u32_e32 v2, 0x100, v2
	global_atomic_add v2, v4, s[66:67] offset:1024
.LBB0_78:
	s_or_b64 exec, exec, s[4:5]
	s_mov_b64 s[4:5], exec
	v_mbcnt_lo_u32_b32 v2, s4, 0
	v_mbcnt_hi_u32_b32 v2, s5, v2
	v_cmp_eq_u32_e32 vcc, 0, v2
	s_waitcnt vmcnt(0)
	s_and_saveexec_b64 s[6:7], vcc
	s_cbranch_execz .LBB0_80
	s_bcnt1_i32_b64 s4, s[4:5]
	v_mov_b32_e32 v2, 0x2000
	v_mov_b32_e32 v3, s4
.LBB0_80:
	s_or_b64 exec, exec, s[6:7]
	s_waitcnt vmcnt(0)

.LBB0_207:
	s_or_b64 exec, exec, s[6:7]
	v_cvt_f32_u32_e32 v5, v2
	s_waitcnt vmcnt(0)
	v_readfirstlane_b32 s4, v4
	s_add_u32 s6, s2, 0x2400
	s_addc_u32 s7, s3, 0
	v_rcp_iflag_f32_e32 v5, v5
	v_add_u32_e32 v3, s4, v3
	v_add_u32_e32 v6, 1, v3
	s_mov_b64 s[8:9], -1
	v_mul_f32_e32 v4, 0x4f7ffffe, v5
	v_cvt_u32_f32_e32 v4, v4
	v_sub_u32_e32 v5, 0, v2
	v_mul_lo_u32 v5, v5, v4
	v_mul_hi_u32 v5, v4, v5
	v_add_u32_e32 v4, v4, v5
	v_mul_hi_u32 v4, v3, v4
	v_mul_lo_u32 v5, v4, v2
	v_sub_u32_e32 v3, v3, v5
	v_add_u32_e32 v7, 1, v4
	v_cmp_ge_u32_e32 vcc, v3, v2
	v_sub_u32_e32 v5, v3, v2
	s_nop 0
	v_cndmask_b32_e32 v4, v4, v7, vcc
	v_cndmask_b32_e32 v3, v3, v5, vcc
	v_add_u32_e32 v5, 1, v4
	v_cmp_ge_u32_e32 vcc, v3, v2
	s_nop 1
	v_cndmask_b32_e32 v4, v4, v5, vcc
	v_mul_lo_u32 v3, v2, v4
	v_add_u32_e32 v2, v3, v2
	v_cmp_ne_u32_e32 vcc, v6, v2
	v_mov_b64_e32 v[2:3], s[6:7]
	s_and_saveexec_b64 s[4:5], vcc
	s_cbranch_execz .LBB0_219
	v_mov_b32_e32 v2, 0
	global_load_dword v3, v2, s[6:7] sc1
	s_mov_b64 s[12:13], 0
	s_waitcnt vmcnt(0)
	v_cmp_eq_u32_e32 vcc, v3, v4
	s_and_saveexec_b64 s[10:11], vcc
	s_cbranch_execz .LBB0_218
	s_add_u32 s8, s82, 0x4200
	s_addc_u32 s9, s83, 0
	s_mov_b32 s22, 1
	s_branch .LBB0_211

.LBB0_221:
	s_or_b64 exec, exec, s[4:5]
	s_mov_b64 s[4:5], exec
	v_mbcnt_lo_u32_b32 v2, s4, 0
	v_mbcnt_hi_u32_b32 v2, s5, v2
	v_cmp_eq_u32_e32 vcc, 0, v2
	s_waitcnt vmcnt(0)
	s_and_saveexec_b64 s[6:7], vcc
	s_cbranch_execz .LBB0_223
	s_bcnt1_i32_b64 s4, s[4:5]
	v_mov_b32_e32 v2, 0x2000
	v_mov_b32_e32 v3, s4
.LBB0_223:
	s_or_b64 exec, exec, s[6:7]
	s_waitcnt vmcnt(0)

.LBB0_360:
	s_or_b64 exec, exec, s[4:5]
	s_mov_b64 s[4:5], exec
	v_mbcnt_lo_u32_b32 v2, s4, 0
	v_mbcnt_hi_u32_b32 v2, s5, v2
	v_cmp_eq_u32_e32 vcc, 0, v2
	s_waitcnt vmcnt(0)
	s_and_saveexec_b64 s[6:7], vcc
	s_cbranch_execz .LBB0_362
	s_bcnt1_i32_b64 s4, s[4:5]
	v_mov_b32_e32 v2, 0x2000
	v_mov_b32_e32 v3, s4
.LBB0_362:
	s_or_b64 exec, exec, s[6:7]
	s_waitcnt vmcnt(0)

.LBB0_494:
	s_or_b64 exec, exec, s[8:9]
	v_cvt_f32_u32_e32 v5, v2
	s_waitcnt vmcnt(0)
	v_readfirstlane_b32 s6, v4
	s_add_u32 s8, s2, 0x2400
	s_addc_u32 s9, s3, 0
	v_rcp_iflag_f32_e32 v5, v5
	v_add_u32_e32 v3, s6, v3
	v_add_u32_e32 v6, 1, v3
	s_mov_b64 s[12:13], -1
	v_mul_f32_e32 v4, 0x4f7ffffe, v5
	v_cvt_u32_f32_e32 v4, v4
	v_sub_u32_e32 v5, 0, v2
	v_mul_lo_u32 v5, v5, v4
	v_mul_hi_u32 v5, v4, v5
	v_add_u32_e32 v4, v4, v5
	v_mul_hi_u32 v4, v3, v4
	v_mul_lo_u32 v5, v4, v2
	v_sub_u32_e32 v3, v3, v5
	v_add_u32_e32 v7, 1, v4
	v_cmp_ge_u32_e32 vcc, v3, v2
	v_sub_u32_e32 v5, v3, v2
	s_nop 0
	v_cndmask_b32_e32 v4, v4, v7, vcc
	v_cndmask_b32_e32 v3, v3, v5, vcc
	v_add_u32_e32 v5, 1, v4
	v_cmp_ge_u32_e32 vcc, v3, v2
	s_nop 1
	v_cndmask_b32_e32 v4, v4, v5, vcc
	v_mul_lo_u32 v3, v2, v4
	v_add_u32_e32 v2, v3, v2
	v_cmp_ne_u32_e32 vcc, v6, v2
	v_mov_b64_e32 v[2:3], s[8:9]
	s_and_saveexec_b64 s[6:7], vcc
	s_cbranch_execz .LBB0_506
	v_mov_b32_e32 v2, 0
	global_load_dword v3, v2, s[8:9] sc1
	s_mov_b64 s[16:17], 0
	s_waitcnt vmcnt(0)
	v_cmp_eq_u32_e32 vcc, v3, v4
	s_and_saveexec_b64 s[14:15], vcc
	s_cbranch_execz .LBB0_505
	s_add_u32 s12, s82, 0x4200
	s_addc_u32 s13, s83, 0
	s_mov_b32 s26, 1
	s_branch .LBB0_498

.LBB0_506:
	s_or_b64 exec, exec, s[6:7]
	s_and_saveexec_b64 s[6:7], s[12:13]
	s_cbranch_execz .LBB0_508
	v_mov_b32_e32 v4, 1
	v_mov_b32_e32 v2, 0x2000
	global_atomic_add v2, v4, s[66:67] offset:1024
	v_add_u32_e32 v2, 0x100, v2
	global_atomic_add v2, v4, s[66:67] offset:1024
	v_add_u32_e32 v2, 0x100, v2
	global_atomic_add v2, v4, s[66:67] offset:1024
	v_add_u32_e32 v2, 0x100, v2
	global_atomic_add v2, v4, s[66:67] offset:1024
	v_add_u32_e32 v2, 0x100, v2
	global_atomic_add v2, v4, s[66:67] offset:1024
	v_add_u32_e32 v2, 0x100, v2
	global_atomic_add v2, v4, s[66:67] offset:1024
	v_add_u32_e32 v2, 0x100, v2
	global_atomic_add v2, v4, s[66:67] offset:1024
	v_add_u32_e32 v2, 0x100, v2
	global_atomic_add v2, v4, s[66:67] offset:1024
	v_add_u32_e32 v2, 0x100, v2
	global_atomic_add v2, v4, s[66:67] offset:1024
	v_add_u32_e32 v2, 0x100, v2
	global_atomic_add v2, v4, s[66:67] offset:1024
	v_add_u32_e32 v2, 0x100, v2
	global_atomic_add v2, v4, s[66:67] offset:1024
	v_add_u32_e32 v2, 0x100, v2
	global_atomic_add v2, v4, s[66:67] offset:1024
	v_add_u32_e32 v2, 0x100, v2
	global_atomic_add v2, v4, s[66:67] offset:1024
	v_add_u32_e32 v2, 0x100, v2
	global_atomic_add v2, v4, s[66:67] offset:1024
	v_add_u32_e32 v2, 0x100, v2
	global_atomic_add v2, v4, s[66:67] offset:1024
	v_add_u32_e32 v2, 0x100, v2
	global_atomic_add v2, v4, s[66:67] offset:1024
.LBB0_508:
	s_or_b64 exec, exec, s[6:7]
	s_mov_b64 s[6:7], exec
	v_mbcnt_lo_u32_b32 v2, s6, 0
	v_mbcnt_hi_u32_b32 v2, s7, v2
	v_cmp_eq_u32_e32 vcc, 0, v2
	s_waitcnt vmcnt(0)
	s_and_saveexec_b64 s[8:9], vcc
	s_cbranch_execz .LBB0_510
	s_bcnt1_i32_b64 s6, s[6:7]
	v_mov_b32_e32 v2, 0x2000
	v_mov_b32_e32 v3, s6
.LBB0_510:
	s_or_b64 exec, exec, s[8:9]
	s_waitcnt vmcnt(0)

.LBB0_617:
	s_or_b64 exec, exec, s[6:7]
	s_mov_b64 s[6:7], exec
	v_mbcnt_lo_u32_b32 v2, s6, 0
	v_mbcnt_hi_u32_b32 v2, s7, v2
	v_cmp_eq_u32_e32 vcc, 0, v2
	s_waitcnt vmcnt(0)
	s_and_saveexec_b64 s[8:9], vcc
	s_cbranch_execz .LBB0_619
	s_bcnt1_i32_b64 s6, s[6:7]
	v_mov_b32_e32 v2, 0x2000
	v_mov_b32_e32 v3, s6
.LBB0_619:
	s_or_b64 exec, exec, s[8:9]
	s_waitcnt vmcnt(0)
